# sum-of-squares v_fmac rewrite also in the layer-0 in-projection GEMM k-loop (phase 1)
# speedup vs baseline: 1.0602x; 1.0011x over previous
; #define G_LOAD(kt_) do { \
;     if constexpr (AF32) { _Pragma("unroll") for (int i = 0; i < 4; ++i) ld16_sc1(ra[i], Af + (size_t)i * 32 * lda + (kt_) * 32); } \
;     else { _Pragma("unroll") for (int i = 0; i < 2; ++i) ld16_sc1(rab[i], Ab + (size_t)i * 64 * lda + (kt_) * 32); } \
;     _Pragma("unroll") for (int i = 0; i < 4; ++i) ld16_sc1(rb[i], Bp + (size_t)(kt_) * bstep + i * 2048); } while (0)
; template <bool AF32, class Epi>
; __device__ __forceinline__ void gemm_tile(unsigned char* smem, const void* Ap, int lda, const bf16_t* WT, int N, int K, const Epi& epi, int m0, int n0,
;                                           GPre& pr, bool preloaded, const void* nAp, int nn0, bool has_next) {
;     ...
;   for (int kt = 0; kt < nk; ++kt) {
;     const int cur = kt & 1;
;     if (kt + 1 < nk) G_STORE(cur ^ 1);
;     if (kt + 2 < nk) G_LOAD(kt + 2);
;     const bf16_t* a_s = sbase + cur * G_STAGE + (wr * 64 + l15) * GLD + quad * 8;
;     const bf16_t* b_s = sbase + cur * G_STAGE + 128 * GLD + (wc * 128 + l15) * GLD + quad * 8;
;     __builtin_amdgcn_s_setprio(1);
;     bf16x8 af[4];
; #pragma unroll
;     for (int m = 0; m < 4; ++m) af[m] = *(const bf16x8*)(a_s + m * 16 * GLD);
; #pragma unroll
;     for (int nh = 0; nh < 4; ++nh) {
;       bf16x8 bfr[2];
; #pragma unroll
;       for (int n2 = 0; n2 < 2; ++n2) bfr[n2] = *(const bf16x8*)(b_s + (nh * 2 + n2) * 16 * GLD);
; #pragma unroll
;       for (int m = 0; m < 4; ++m)
; #pragma unroll
;         for (int n2 = 0; n2 < 2; ++n2) acc[m][nh * 2 + n2] = __builtin_amdgcn_mfma_f32_16x16x32_bf16(bfr[n2], af[m], acc[m][nh * 2 + n2], 0, 0, 0);
;     }
;     __builtin_amdgcn_s_setprio(0);
;     __syncthreads();
;   }
.LBB0_126:
	s_and_b32 s3, s12, 1
	s_waitcnt vmcnt(0)
	s_xor_b32 s4, s3, 1
	s_mulk_i32 s4, 0x7800
	v_lshl_add_u32 v208, v170, 1, s4
	ds_write_b128 v208, v[32:35] offset:10240
	ds_write_b128 v208, v[36:39] offset:15360
	ds_write_b128 v208, v[40:43] offset:20480
	ds_write_b128 v208, v[48:51] offset:25600
	s_setprio 2
	global_load_dwordx4 v[32:35], v[172:173], off sc1
	v_lshl_add_u64 v[192:193], v[172:173], 0, s[30:31]
	global_load_dwordx4 v[36:39], v[192:193], off sc1
	v_lshl_add_u64 v[194:195], v[172:173], 0, s[34:35]
	global_load_dwordx4 v[40:43], v[194:195], off sc1
	v_lshl_add_u64 v[196:197], v[172:173], 0, s[36:37]
	global_load_dwordx4 v[48:51], v[196:197], off sc1
	s_setprio 0
	v_lshl_add_u32 v185, v181, 1, s4
	v_fmac_f32_e32 v169, v16, v16
	v_fmac_f32_e32 v168, v8, v8
	v_fmac_f32_e32 v165, v4, v4
	v_fmac_f32_e32 v164, v0, v0
	v_fmac_f32_e32 v169, v17, v17
	v_fmac_f32_e32 v168, v9, v9
	v_fmac_f32_e32 v165, v5, v5
	v_fmac_f32_e32 v164, v1, v1
	v_fmac_f32_e32 v169, v18, v18
	v_fmac_f32_e32 v168, v10, v10
	v_fmac_f32_e32 v165, v6, v6
	v_fmac_f32_e32 v164, v2, v2
	v_fmac_f32_e32 v169, v19, v19
	v_fmac_f32_e32 v168, v11, v11
	v_fmac_f32_e32 v165, v7, v7
	v_fmac_f32_e32 v164, v3, v3
	v_cvt_pk_bf16_f32 v198, v16, v17
	v_cvt_pk_bf16_f32 v199, v18, v19
	v_cvt_pk_bf16_f32 v8, v8, v9
	v_cvt_pk_bf16_f32 v9, v10, v11
	v_cvt_pk_bf16_f32 v10, v4, v5
	v_cvt_pk_bf16_f32 v11, v6, v7
	v_cvt_pk_bf16_f32 v0, v0, v1
	v_cvt_pk_bf16_f32 v1, v2, v3
	ds_write2st64_b64 v185, v[198:199], v[8:9] offset1:5
	ds_write2st64_b64 v185, v[10:11], v[0:1] offset0:10 offset1:15
	s_setprio 2
	global_load_dwordx4 v[16:19], v[174:175], off sc1
	v_lshl_add_u64 v[186:187], v[174:175], 0, s[26:27]
	global_load_dwordx4 v[8:11], v[186:187], off sc1
	v_lshl_add_u64 v[188:189], v[174:175], 0, s[28:29]
	global_load_dwordx4 v[4:7], v[188:189], off sc1
	v_lshl_add_u64 v[190:191], v[174:175], 0, s[22:23]
	global_load_dwordx4 v[0:3], v[190:191], off sc1
	s_setprio 0
	s_add_i32 s12, s12, 1
	s_mulk_i32 s3, 0x7800
	v_add3_u32 v185, s3, v166, v184
	s_setprio 1
	v_add3_u32 v212, s3, v183, v184
	ds_read_b128 v[186:189], v212 offset:10240
	ds_read_b128 v[190:193], v212 offset:11520
	ds_read_b128 v[194:197], v185
	ds_read_b128 v[198:201], v185 offset:1280
	ds_read_b128 v[202:205], v185 offset:2560
	ds_read_b128 v[206:209], v185 offset:3840
	s_waitcnt lgkmcnt(3)
	v_mfma_f32_16x16x32_bf16 v[156:159], v[186:189], v[194:197], v[156:159]
	v_mfma_f32_16x16x32_bf16 v[152:155], v[190:193], v[194:197], v[152:155]
	s_waitcnt lgkmcnt(2)
	v_mfma_f32_16x16x32_bf16 v[140:143], v[186:189], v[198:201], v[140:143]
	v_mfma_f32_16x16x32_bf16 v[136:139], v[190:193], v[198:201], v[136:139]
	s_waitcnt lgkmcnt(1)
	v_mfma_f32_16x16x32_bf16 v[108:111], v[186:189], v[202:205], v[108:111]
	v_mfma_f32_16x16x32_bf16 v[100:103], v[190:193], v[202:205], v[100:103]
	s_waitcnt lgkmcnt(0)
	v_mfma_f32_16x16x32_bf16 v[76:79], v[186:189], v[206:209], v[76:79]
	ds_read_b128 v[186:189], v212 offset:12800
	v_mfma_f32_16x16x32_bf16 v[68:71], v[190:193], v[206:209], v[68:71]
	ds_read_b128 v[190:193], v212 offset:14080
	s_waitcnt lgkmcnt(1)
	v_mfma_f32_16x16x32_bf16 v[148:151], v[186:189], v[194:197], v[148:151]
	s_waitcnt lgkmcnt(0)
	v_mfma_f32_16x16x32_bf16 v[144:147], v[190:193], v[194:197], v[144:147]
	v_mfma_f32_16x16x32_bf16 v[124:127], v[186:189], v[198:201], v[124:127]
	v_mfma_f32_16x16x32_bf16 v[116:119], v[190:193], v[198:201], v[116:119]
	v_mfma_f32_16x16x32_bf16 v[92:95], v[186:189], v[202:205], v[92:95]
	v_mfma_f32_16x16x32_bf16 v[84:87], v[190:193], v[202:205], v[84:87]
	v_mfma_f32_16x16x32_bf16 v[60:63], v[186:189], v[206:209], v[60:63]
	ds_read_b128 v[186:189], v212 offset:15360
	v_mfma_f32_16x16x32_bf16 v[52:55], v[190:193], v[206:209], v[52:55]
	ds_read_b128 v[190:193], v212 offset:16640
	s_waitcnt lgkmcnt(1)
	v_mfma_f32_16x16x32_bf16 v[132:135], v[186:189], v[194:197], v[132:135]
	s_waitcnt lgkmcnt(0)
	v_mfma_f32_16x16x32_bf16 v[128:131], v[190:193], v[194:197], v[128:131]
	v_mfma_f32_16x16x32_bf16 v[104:107], v[186:189], v[198:201], v[104:107]
	v_mfma_f32_16x16x32_bf16 v[96:99], v[190:193], v[198:201], v[96:99]
	v_mfma_f32_16x16x32_bf16 v[72:75], v[186:189], v[202:205], v[72:75]
	v_mfma_f32_16x16x32_bf16 v[64:67], v[190:193], v[202:205], v[64:67]
	v_mfma_f32_16x16x32_bf16 v[28:31], v[186:189], v[206:209], v[28:31]
	ds_read_b128 v[186:189], v212 offset:17920
	v_mfma_f32_16x16x32_bf16 v[24:27], v[190:193], v[206:209], v[24:27]
	ds_read_b128 v[190:193], v212 offset:19200
	s_waitcnt lgkmcnt(1)
	v_mfma_f32_16x16x32_bf16 v[120:123], v[186:189], v[194:197], v[120:123]
	s_waitcnt lgkmcnt(0)
	v_mfma_f32_16x16x32_bf16 v[112:115], v[190:193], v[194:197], v[112:115]
	v_mfma_f32_16x16x32_bf16 v[88:91], v[186:189], v[198:201], v[88:91]
	v_mfma_f32_16x16x32_bf16 v[80:83], v[190:193], v[198:201], v[80:83]
	v_mfma_f32_16x16x32_bf16 v[56:59], v[186:189], v[202:205], v[56:59]
	v_mfma_f32_16x16x32_bf16 v[44:47], v[190:193], v[202:205], v[44:47]
	v_mfma_f32_16x16x32_bf16 v[20:23], v[186:189], v[206:209], v[20:23]
	v_mfma_f32_16x16x32_bf16 v[12:15], v[190:193], v[206:209], v[12:15]
	s_setprio 0
	v_lshl_add_u64 v[172:173], v[172:173], 0, s[26:27]
	s_cmp_eq_u32 s12, 30
	v_lshl_add_u64 v[174:175], v[174:175], 0, s[38:39]
	s_barrier
	s_cbranch_scc0 .LBB0_126
; #define G_LOAD(kt_) do { \
;     if constexpr (AF32) { _Pragma("unroll") for (int i = 0; i < 4; ++i) ld16_sc1(ra[i], Af + (size_t)i * 32 * lda + (kt_) * 32); } \
;     else { _Pragma("unroll") for (int i = 0; i < 2; ++i) ld16_sc1(rab[i], Ab + (size_t)i * 64 * lda + (kt_) * 32); } \
;     _Pragma("unroll") for (int i = 0; i < 4; ++i) ld16_sc1(rb[i], Bp + (size_t)(kt_) * bstep + i * 2048); } while (0)
; template <bool AF32, class Epi>
; __device__ __forceinline__ void gemm_tile(unsigned char* smem, const void* Ap, int lda, const bf16_t* WT, int N, int K, const Epi& epi, int m0, int n0,
;                                           GPre& pr, bool preloaded, const void* nAp, int nn0, bool has_next) {
;     ...
;   if (!preloaded) G_LOAD(0);
;   G_STORE(0);
;   if (nk > 1) G_LOAD(1);
;   __syncthreads();
;   for (int kt = 0; kt < nk; ++kt) {
;     const int cur = kt & 1;
;     if (kt + 1 < nk) G_STORE(cur ^ 1);
;     if (kt + 2 < nk) G_LOAD(kt + 2);
;     const bf16_t* a_s = sbase + cur * G_STAGE + (wr * 64 + l15) * GLD + quad * 8;
;     const bf16_t* b_s = sbase + cur * G_STAGE + 128 * GLD + (wc * 128 + l15) * GLD + quad * 8;
;     __builtin_amdgcn_s_setprio(1);
;     bf16x8 af[4];
; #pragma unroll
;     for (int m = 0; m < 4; ++m) af[m] = *(const bf16x8*)(a_s + m * 16 * GLD);
; #pragma unroll
;     for (int nh = 0; nh < 4; ++nh) {
;       bf16x8 bfr[2];
; #pragma unroll
;       for (int n2 = 0; n2 < 2; ++n2) bfr[n2] = *(const bf16x8*)(b_s + (nh * 2 + n2) * 16 * GLD);
; #pragma unroll
;       for (int m = 0; m < 4; ++m)
; #pragma unroll
;         for (int n2 = 0; n2 < 2; ++n2) acc[m][nh * 2 + n2] = __builtin_amdgcn_mfma_f32_16x16x32_bf16(bfr[n2], af[m], acc[m][nh * 2 + n2], 0, 0, 0);
;     }
;     __builtin_amdgcn_s_setprio(0);
;     __syncthreads();
	s_waitcnt vmcnt(0)
	s_nop 0
	v_cvt_pk_bf16_f32 v172, v16, v17
	v_mul_f32_e32 v17, v17, v17
	v_fmac_f32_e32 v17, v16, v16
	v_cvt_pk_bf16_f32 v173, v18, v19
	v_cvt_pk_bf16_f32 v174, v8, v9
	v_cvt_pk_bf16_f32 v175, v10, v11
	v_fmac_f32_e32 v17, v18, v18
	ds_write2st64_b64 v171, v[172:173], v[174:175] offset0:60 offset1:65
	v_cvt_pk_bf16_f32 v172, v4, v5
	v_cvt_pk_bf16_f32 v173, v6, v7
	v_cvt_pk_bf16_f32 v174, v0, v1
	v_cvt_pk_bf16_f32 v175, v2, v3
	v_fmac_f32_e32 v17, v19, v19
	ds_write2st64_b64 v171, v[172:173], v[174:175] offset0:70 offset1:75
	ds_write_b128 v182, v[32:35] offset:40960
	ds_write_b128 v182, v[36:39] offset:46080
	ds_write_b128 v182, v[40:43] offset:51200
	ds_write_b128 v182, v[48:51] offset:56320
	v_add_f32_e32 v169, v169, v17
	v_add_u32_e32 v174, v166, v184
	s_setprio 1
	v_add_u32_e32 v175, v183, v184
	ds_read_b128 v[16:19], v175 offset:10240
	ds_read_b128 v[32:35], v175 offset:11520
	ds_read_b128 v[36:39], v174
	ds_read_b128 v[40:43], v174 offset:1280
	s_waitcnt lgkmcnt(1)
	v_mfma_f32_16x16x32_bf16 v[48:51], v[16:19], v[36:39], v[156:159]
	s_waitcnt lgkmcnt(0)
	v_mfma_f32_16x16x32_bf16 v[156:159], v[32:35], v[40:43], v[136:139]
	s_nop 2
	ds_read_b128 v[136:139], v174 offset:2560
	ds_read_b128 v[170:173], v174 offset:3840
	v_mfma_f32_16x16x32_bf16 v[152:155], v[32:35], v[36:39], v[152:155]
	v_mfma_f32_16x16x32_bf16 v[140:143], v[16:19], v[40:43], v[140:143]
	s_waitcnt lgkmcnt(1)
	v_mfma_f32_16x16x32_bf16 v[108:111], v[16:19], v[136:139], v[108:111]
	v_mfma_f32_16x16x32_bf16 v[100:103], v[32:35], v[136:139], v[100:103]
	s_waitcnt lgkmcnt(0)
	v_mfma_f32_16x16x32_bf16 v[16:19], v[16:19], v[170:173], v[76:79]
	s_nop 2
	ds_read_b128 v[76:79], v175 offset:12800
	v_mfma_f32_16x16x32_bf16 v[32:35], v[32:35], v[170:173], v[68:71]
	s_nop 2
	ds_read_b128 v[68:71], v175 offset:14080
	s_waitcnt lgkmcnt(1)
	v_mfma_f32_16x16x32_bf16 v[148:151], v[76:79], v[36:39], v[148:151]
	s_waitcnt lgkmcnt(0)
	v_mfma_f32_16x16x32_bf16 v[144:147], v[68:71], v[36:39], v[144:147]
	v_mfma_f32_16x16x32_bf16 v[124:127], v[76:79], v[40:43], v[124:127]
	v_mfma_f32_16x16x32_bf16 v[116:119], v[68:71], v[40:43], v[116:119]
	v_mfma_f32_16x16x32_bf16 v[92:95], v[76:79], v[136:139], v[92:95]
	v_mfma_f32_16x16x32_bf16 v[84:87], v[68:71], v[136:139], v[84:87]
	v_mfma_f32_16x16x32_bf16 v[60:63], v[76:79], v[170:173], v[60:63]
	ds_read_b128 v[76:79], v175 offset:15360
	v_mfma_f32_16x16x32_bf16 v[52:55], v[68:71], v[170:173], v[52:55]
	ds_read_b128 v[68:71], v175 offset:16640
	s_waitcnt lgkmcnt(1)
	v_mfma_f32_16x16x32_bf16 v[182:185], v[76:79], v[36:39], v[132:135]
	v_mfma_f32_16x16x32_bf16 v[190:193], v[76:79], v[40:43], v[104:107]
	v_mfma_f32_16x16x32_bf16 v[198:201], v[76:79], v[136:139], v[72:75]
	v_mfma_f32_16x16x32_bf16 v[76:79], v[76:79], v[170:173], v[28:31]
	s_nop 2
	ds_read_b128 v[28:31], v175 offset:17920
	s_waitcnt lgkmcnt(1)
	v_mfma_f32_16x16x32_bf16 v[206:209], v[68:71], v[170:173], v[24:27]
	s_nop 2
	ds_read_b128 v[24:27], v175 offset:19200
	s_waitcnt lgkmcnt(0)
	v_mfma_f32_16x16x32_bf16 v[44:47], v[24:27], v[136:139], v[44:47]
	v_mfma_f32_16x16x32_bf16 v[12:15], v[24:27], v[170:173], v[12:15]
	v_mfma_f32_16x16x32_bf16 v[186:189], v[68:71], v[36:39], v[128:131]
	v_mfma_f32_16x16x32_bf16 v[194:197], v[68:71], v[40:43], v[96:99]
	v_mfma_f32_16x16x32_bf16 v[202:205], v[68:71], v[136:139], v[64:67]
	v_mfma_f32_16x16x32_bf16 v[212:215], v[28:31], v[36:39], v[120:123]
	v_mfma_f32_16x16x32_bf16 v[216:219], v[24:27], v[36:39], v[112:115]
	v_mfma_f32_16x16x32_bf16 v[220:223], v[28:31], v[40:43], v[88:91]
	v_mfma_f32_16x16x32_bf16 v[224:227], v[24:27], v[40:43], v[80:83]
	v_mfma_f32_16x16x32_bf16 v[228:231], v[28:31], v[136:139], v[56:59]
	v_mfma_f32_16x16x32_bf16 v[232:235], v[28:31], v[170:173], v[20:23]
	s_setprio 0
	s_barrier
; #define G_LOAD(kt_) do { \
;     if constexpr (AF32) { _Pragma("unroll") for (int i = 0; i < 4; ++i) ld16_sc1(ra[i], Af + (size_t)i * 32 * lda + (kt_) * 32); } \
;     else { _Pragma("unroll") for (int i = 0; i < 2; ++i) ld16_sc1(rab[i], Ab + (size_t)i * 64 * lda + (kt_) * 32); } \
;     _Pragma("unroll") for (int i = 0; i < 4; ++i) ld16_sc1(rb[i], Bp + (size_t)(kt_) * bstep + i * 2048); } while (0)
; template <bool AF32, class Epi>
; __device__ __forceinline__ void gemm_tile(unsigned char* smem, const void* Ap, int lda, const bf16_t* WT, int N, int K, const Epi& epi, int m0, int n0,
;                                           GPre& pr, bool preloaded, const void* nAp, int nn0, bool has_next) {
;     ...
;   for (int kt = 0; kt < nk; ++kt) {
;     const int cur = kt & 1;
;     if (kt + 1 < nk) G_STORE(cur ^ 1);
;     if (kt + 2 < nk) G_LOAD(kt + 2);
;     const bf16_t* a_s = sbase + cur * G_STAGE + (wr * 64 + l15) * GLD + quad * 8;
;     const bf16_t* b_s = sbase + cur * G_STAGE + 128 * GLD + (wc * 128 + l15) * GLD + quad * 8;
;     __builtin_amdgcn_s_setprio(1);
;     bf16x8 af[4];
; #pragma unroll
;     for (int m = 0; m < 4; ++m) af[m] = *(const bf16x8*)(a_s + m * 16 * GLD);
; #pragma unroll
;     for (int nh = 0; nh < 4; ++nh) {
;       bf16x8 bfr[2];
; #pragma unroll
;       for (int n2 = 0; n2 < 2; ++n2) bfr[n2] = *(const bf16x8*)(b_s + (nh * 2 + n2) * 16 * GLD);
; #pragma unroll
;       for (int m = 0; m < 4; ++m)
; #pragma unroll
;         for (int n2 = 0; n2 < 2; ++n2) acc[m][nh * 2 + n2] = __builtin_amdgcn_mfma_f32_16x16x32_bf16(bfr[n2], af[m], acc[m][nh * 2 + n2], 0, 0, 0);
;     }
;     __builtin_amdgcn_s_setprio(0);
;     __syncthreads();
;   }
;   if (has_next) {
;     const float* Af = (const float*)nAp + (size_t)(tid >> 3) * lda + (tid & 7) * 4;
;     const bf16_t* Ab = (const bf16_t*)nAp + (size_t)(tid >> 2) * lda + (tid & 3) * 8;
;     const bf16_t* Bp = WT + (size_t)nn0 * 32 + tid * 8;
;     G_LOAD(0);
;   }
;     ...
;   if constexpr (AF32) {
;     const float invK = 1.0f / (float)K;
; #pragma unroll
;     for (int i = 0; i < 4; ++i) {
;       float s = ss[i];
;       s += __shfl_xor(s, 1); s += __shfl_xor(s, 2); s += __shfl_xor(s, 4);
;       if ((tid & 7) == 0) sR[(tid >> 3) + 32 * i] = rsqrtf(s * invK + EPS);
;     }
	s_setprio 1
	ds_read_b128 v[20:23], v175 offset:40960
	ds_read_b128 v[24:27], v175 offset:42240
	ds_read_b128 v[170:173], v174 offset:30720
	ds_read_b128 v[236:239], v174 offset:32000
	s_waitcnt lgkmcnt(1)
	v_mfma_f32_16x16x32_bf16 v[128:131], v[24:27], v[170:173], v[152:155]
	s_waitcnt lgkmcnt(0)
	v_mfma_f32_16x16x32_bf16 v[104:107], v[20:23], v[236:239], v[140:143]
	s_nop 2
	ds_read_b128 v[140:143], v174 offset:33280
	ds_read_b128 v[152:155], v174 offset:34560
	s_waitcnt lgkmcnt(0)
	v_mfma_f32_16x16x32_bf16 v[40:43], v[20:23], v[152:155], v[16:19]
	s_nop 2
	ds_read_b128 v[16:19], v175 offset:43520
	v_mfma_f32_16x16x32_bf16 v[136:139], v[20:23], v[170:173], v[48:51]
	v_mfma_f32_16x16x32_bf16 v[72:75], v[20:23], v[140:143], v[108:111]
	ds_read_b128 v[20:23], v175 offset:44800
	v_mfma_f32_16x16x32_bf16 v[64:67], v[24:27], v[140:143], v[100:103]
	v_mfma_f32_16x16x32_bf16 v[36:39], v[24:27], v[152:155], v[32:35]
	s_waitcnt lgkmcnt(1)
	v_mfma_f32_16x16x32_bf16 v[132:135], v[16:19], v[170:173], v[148:151]
	v_mfma_f32_16x16x32_bf16 v[100:103], v[16:19], v[236:239], v[124:127]
	v_mfma_f32_16x16x32_bf16 v[68:71], v[16:19], v[140:143], v[92:95]
	v_mfma_f32_16x16x32_bf16 v[32:35], v[16:19], v[152:155], v[60:63]
	ds_read_b128 v[16:19], v175 offset:46080
	v_mfma_f32_16x16x32_bf16 v[96:99], v[24:27], v[236:239], v[156:159]
	s_waitcnt lgkmcnt(1)
	v_mfma_f32_16x16x32_bf16 v[120:123], v[20:23], v[170:173], v[144:147]
	v_mfma_f32_16x16x32_bf16 v[88:91], v[20:23], v[236:239], v[116:119]
	s_nop 1
	ds_read_b128 v[144:147], v175 offset:49920
	v_mfma_f32_16x16x32_bf16 v[56:59], v[20:23], v[140:143], v[84:87]
	v_mfma_f32_16x16x32_bf16 v[28:31], v[20:23], v[152:155], v[52:55]
	ds_read_b128 v[20:23], v175 offset:47360
	s_waitcnt lgkmcnt(2)
	v_mfma_f32_16x16x32_bf16 v[124:127], v[16:19], v[170:173], v[182:185]
	v_mfma_f32_16x16x32_bf16 v[92:95], v[16:19], v[236:239], v[190:193]
	v_mfma_f32_16x16x32_bf16 v[60:63], v[16:19], v[140:143], v[198:201]
	v_mfma_f32_16x16x32_bf16 v[24:27], v[16:19], v[152:155], v[76:79]
	ds_read_b128 v[16:19], v175 offset:48640
	s_waitcnt lgkmcnt(1)
	v_mfma_f32_16x16x32_bf16 v[112:115], v[20:23], v[170:173], v[186:189]
	v_mfma_f32_16x16x32_bf16 v[80:83], v[20:23], v[236:239], v[194:197]
	v_mfma_f32_16x16x32_bf16 v[48:51], v[20:23], v[140:143], v[202:205]
	v_mfma_f32_16x16x32_bf16 v[20:23], v[20:23], v[152:155], v[206:209]
	s_waitcnt lgkmcnt(0)
	v_mfma_f32_16x16x32_bf16 v[116:119], v[16:19], v[170:173], v[212:215]
	v_mfma_f32_16x16x32_bf16 v[108:111], v[144:147], v[170:173], v[216:219]
	v_mfma_f32_16x16x32_bf16 v[84:87], v[16:19], v[236:239], v[220:223]
	v_mfma_f32_16x16x32_bf16 v[76:79], v[144:147], v[236:239], v[224:227]
	v_mfma_f32_16x16x32_bf16 v[52:55], v[16:19], v[140:143], v[228:231]
	v_mfma_f32_16x16x32_bf16 v[44:47], v[144:147], v[140:143], v[44:47]
	v_mfma_f32_16x16x32_bf16 v[16:19], v[16:19], v[152:155], v[232:235]
	v_mfma_f32_16x16x32_bf16 v[12:15], v[144:147], v[152:155], v[12:15]
	s_setprio 0
	v_and_b32_e32 v141, 64, v177
	v_xor_b32_e32 v140, 1, v177
	v_add_u32_e32 v141, 64, v141
	v_cmp_lt_i32_e32 vcc, v140, v141
	v_xor_b32_e32 v142, 2, v177
	s_nop 0
	v_cndmask_b32_e32 v140, v177, v140, vcc
	v_lshlrev_b32_e32 v140, 2, v140
	ds_bpermute_b32 v143, v140, v169
	v_cmp_lt_i32_e32 vcc, v142, v141
	s_barrier
	s_waitcnt lgkmcnt(0)
	v_cndmask_b32_e32 v142, v177, v142, vcc
	v_lshlrev_b32_e32 v142, 2, v142
	v_add_f32_e32 v144, v169, v143
	ds_bpermute_b32 v145, v142, v144
	v_xor_b32_e32 v143, 4, v177
	v_cmp_lt_i32_e32 vcc, v143, v141
	s_waitcnt lgkmcnt(0)
	v_add_f32_e32 v144, v144, v145
	v_cndmask_b32_e32 v141, v177, v143, vcc
	v_lshlrev_b32_e32 v143, 2, v141
	ds_bpermute_b32 v145, v143, v144
	v_cmp_eq_u32_e32 vcc, 0, v163
	v_lshlrev_b32_e32 v141, 2, v162
	s_and_saveexec_b64 s[6:7], vcc
	s_cbranch_execz .LBB0_129
	s_waitcnt lgkmcnt(0)
	v_add_f32_e32 v144, v144, v145
	v_fmamk_f32 v144, v144, 0x3a800000, v176
	v_mul_f32_e32 v145, 0x4b800000, v144
	v_cmp_gt_f32_e64 s[4:5], s73, v144
	s_nop 1
	v_cndmask_b32_e64 v144, v144, v145, s[4:5]
	v_rsq_f32_e32 v144, v144
	s_nop 0
	v_mul_f32_e32 v145, 0x45800000, v144
	v_cndmask_b32_e64 v144, v144, v145, s[4:5]
	ds_write_b32 v141, v144 offset:61440
